# adds: sample-row attention loop hand-scheduled like the prompt loop; k_rope tile skips all-padding MFMA groups per wave
# speedup vs baseline: 1.0137x; 1.0063x over previous
; #define PG8_STAGE(bufoff, gbase, voff) do { _Pragma("unroll") for (int _i = 0; _i < 2; ++_i) \
;         __builtin_amdgcn_global_load_lds((const unsigned*)((const char*)(gbase) + (voff)[_i]), (LAS unsigned*)(lds + (bufoff) + ldsw + _i * 8192), 16, 0, 0); } while (0)
; #define PG8_LDA(dst, b, h) do { _Pragma("unroll") for (int m = 0; m < 4; ++m) _Pragma("unroll") for (int k = 0; k < 2; ++k) dst[m][k] = *(const LAS bf16x8*)(lds + PG8_SA(b, h) + aoff + m * 2048 + k * 1024); } while (0)
; #define PG8_LDB(dst, b, h) do { _Pragma("unroll") for (int n = 0; n < 2; ++n) _Pragma("unroll") for (int k = 0; k < 2; ++k) dst[n][k] = *(const LAS bf16x8*)(lds + PG8_SB(b, h) + boff + n * 2048 + k * 1024); } while (0)
; #define PG8_MMA(ai, bj, At, Bt) do { __builtin_amdgcn_s_setprio(1); _Pragma("unroll") for (int m = 0; m < 4; ++m) _Pragma("unroll") for (int n = 0; n < 2; ++n) _Pragma("unroll") for (int k = 0; k < 2; ++k) \
;         acc[ai][bj][m][n] = __builtin_amdgcn_mfma_f32_16x16x32_bf16(Bt[n][k], At[m][k], acc[ai][bj][m][n], 0, 0, 0); __builtin_amdgcn_s_setprio(0); } while (0)
; #define PG8_WAIT_L(n) asm volatile("s_waitcnt lgkmcnt(" #n ")" ::: "memory")
; #define PG8_BAR __builtin_amdgcn_s_barrier()
; #define PG8_SCHED __builtin_amdgcn_sched_barrier(0)
; template <class Epi, class Sched>
; __device__ __forceinline__ void gemm_phase(LAS unsigned char* lds, const int K, const Sched& S, const Epi& E) {
;     ...
;         for (int t = 0; t < nt; t += 2) {
;             const bool last = (t == nt - 2);
;             const char* a1 = cA + (size_t)(t + 1) * kstep;
;             const char* a2 = last ? nA : cA + (size_t)(t + 2) * kstep; const char* b2 = last ? nB : cB + (size_t)(t + 2) * kstep;
;             const char* a3 = a2 + kstep; const char* b3 = b2 + kstep;
;             PG8_LDB(B0, 0, 0); PG8_SCHED; PG8_LDA(At, 0, 0); PG8_STAGE(PG8_SA(1, 1), a1 + hstep, voffA);
;             PG8_WAIT_L(8); PG8_BAR; PG8_WAIT_L(0); PG8_MMA(0, 0, At, B0); PG8_BAR; PG8_SCHED;
;     ...
;         for (int a = 0; a < 2; ++a)
; #pragma unroll
;             for (int b = 0; b < 2; ++b)
; #pragma unroll
;                 for (int m = 0; m < 4; ++m)
; #pragma unroll
;                     for (int n = 0; n < 2; ++n) acc[a][b][m][n] = (f32x4){0.f, 0.f, 0.f, 0.f};
;         cur = nxt; cA = nA; cB = nB; ++ui;
.LBB0_254:
	s_ashr_i32 s53, s52, 31
	s_lshl_b64 s[54:55], s[52:53], 19
	s_add_u32 s54, s33, s54
	s_addc_u32 s55, s70, s55
	s_and_b64 s[56:57], s[66:67], exec
	s_cselect_b32 s12, s55, s63
	s_cselect_b32 s53, s54, s62
	s_ashr_i32 s51, s50, 31
	s_lshl_b64 s[56:57], s[50:51], 19
	s_add_u32 s56, s10, s56
	s_addc_u32 s57, s11, s57
	s_and_b64 s[66:67], s[66:67], exec
	s_cselect_b32 s51, s57, s65
	s_cselect_b32 s59, s56, s64
	s_add_u32 s62, s62, 0x40080
	s_addc_u32 s63, s63, 0
	s_add_u32 s61, s64, 0x100
	v_mov_b32_e32 v0, 0
	s_addc_u32 s93, s65, 0
	s_mov_b32 s94, -2
	v_mov_b32_e32 v1, v0
	v_mov_b32_e32 v2, v0
	v_mov_b32_e32 v3, v0
	v_mov_b32_e32 v4, v0
	s_waitcnt lgkmcnt(0)
	v_mov_b32_e32 v5, v0
	v_mov_b32_e32 v6, v0
	v_mov_b32_e32 v7, v0
	v_mov_b32_e32 v16, v0
	v_mov_b32_e32 v17, v0
	v_mov_b32_e32 v18, v0
	v_mov_b32_e32 v19, v0
	v_mov_b32_e32 v20, v0
	v_mov_b32_e32 v21, v0
	v_mov_b32_e32 v22, v0
	v_mov_b32_e32 v23, v0
	v_mov_b32_e32 v32, v0
	v_mov_b32_e32 v33, v0
	v_mov_b32_e32 v34, v0
	v_mov_b32_e32 v35, v0
	v_mov_b32_e32 v36, v0
	v_mov_b32_e32 v37, v0
	v_mov_b32_e32 v38, v0
	v_mov_b32_e32 v39, v0
	v_mov_b32_e32 v48, v0
	v_mov_b32_e32 v49, v0
	v_mov_b32_e32 v50, v0
	v_mov_b32_e32 v51, v0
	v_mov_b32_e32 v52, v0
	v_mov_b32_e32 v53, v0
	v_mov_b32_e32 v54, v0
	v_mov_b32_e32 v55, v0
	v_mov_b32_e32 v8, v0
	v_mov_b32_e32 v9, v0
	v_mov_b32_e32 v10, v0
	v_mov_b32_e32 v11, v0
	v_mov_b32_e32 v12, v0
	v_mov_b32_e32 v13, v0
	v_mov_b32_e32 v14, v0
	v_mov_b32_e32 v15, v0
	v_mov_b32_e32 v24, v0
	v_mov_b32_e32 v25, v0
	v_mov_b32_e32 v26, v0
	v_mov_b32_e32 v27, v0
	v_mov_b32_e32 v28, v0
	v_mov_b32_e32 v29, v0
	v_mov_b32_e32 v30, v0
	v_mov_b32_e32 v31, v0
	v_mov_b32_e32 v40, v0
	v_mov_b32_e32 v41, v0
	v_mov_b32_e32 v42, v0
	v_mov_b32_e32 v43, v0
	v_mov_b32_e32 v44, v0
	v_mov_b32_e32 v45, v0
	v_mov_b32_e32 v46, v0
	v_mov_b32_e32 v47, v0
	v_mov_b32_e32 v56, v0
	v_mov_b32_e32 v57, v0
	v_mov_b32_e32 v58, v0
	v_mov_b32_e32 v59, v0
	v_mov_b32_e32 v60, v0
	v_mov_b32_e32 v61, v0
	v_mov_b32_e32 v62, v0
	v_mov_b32_e32 v63, v0
	v_mov_b32_e32 v64, v0
	v_mov_b32_e32 v65, v0
	v_mov_b32_e32 v66, v0
	v_mov_b32_e32 v67, v0
	v_mov_b32_e32 v68, v0
	v_mov_b32_e32 v69, v0
	v_mov_b32_e32 v70, v0
	v_mov_b32_e32 v71, v0
	v_mov_b32_e32 v80, v0
	v_mov_b32_e32 v81, v0
	v_mov_b32_e32 v82, v0
	v_mov_b32_e32 v83, v0
	v_mov_b32_e32 v84, v0
	v_mov_b32_e32 v85, v0
	v_mov_b32_e32 v86, v0
	v_mov_b32_e32 v87, v0
	v_mov_b32_e32 v96, v0
	v_mov_b32_e32 v97, v0
	v_mov_b32_e32 v98, v0
	v_mov_b32_e32 v99, v0
	v_mov_b32_e32 v100, v0
	v_mov_b32_e32 v101, v0
	v_mov_b32_e32 v102, v0
	v_mov_b32_e32 v103, v0
	v_mov_b32_e32 v112, v0
	v_mov_b32_e32 v113, v0
	v_mov_b32_e32 v114, v0
	v_mov_b32_e32 v115, v0
	v_mov_b32_e32 v116, v0
	v_mov_b32_e32 v117, v0
	v_mov_b32_e32 v118, v0
	v_mov_b32_e32 v119, v0
	v_mov_b32_e32 v72, v0
	v_mov_b32_e32 v73, v0
	v_mov_b32_e32 v74, v0
	v_mov_b32_e32 v75, v0
	v_mov_b32_e32 v76, v0
	v_mov_b32_e32 v77, v0
	v_mov_b32_e32 v78, v0
	v_mov_b32_e32 v79, v0
	v_mov_b32_e32 v88, v0
	v_mov_b32_e32 v89, v0
	v_mov_b32_e32 v90, v0
	v_mov_b32_e32 v91, v0
	v_mov_b32_e32 v92, v0
	v_mov_b32_e32 v93, v0
	v_mov_b32_e32 v94, v0
	v_mov_b32_e32 v95, v0
	v_mov_b32_e32 v104, v0
	v_mov_b32_e32 v105, v0
	v_mov_b32_e32 v106, v0
	v_mov_b32_e32 v107, v0
	v_mov_b32_e32 v108, v0
	v_mov_b32_e32 v109, v0
	v_mov_b32_e32 v110, v0
	v_mov_b32_e32 v111, v0
	v_mov_b32_e32 v120, v0
	v_mov_b32_e32 v121, v0
	v_mov_b32_e32 v122, v0
	v_mov_b32_e32 v123, v0
	v_mov_b32_e32 v124, v0
	v_mov_b32_e32 v125, v0
	v_mov_b32_e32 v126, v0
	v_mov_b32_e32 v127, v0
	s_cmpk_eq_i32 s58, 0x10
	s_cselect_b32 s101, 1, 0
	s_cmpk_eq_i32 s60, 0x100
	s_cselect_b32 s100, 2, 0
	s_or_b32 s101, s101, s100
	v_readfirstlane_b32 s100, v230
	s_lshr_b32 s100, s100, 5
	s_and_b32 s100, s100, 4
	s_bitcmp1_b32 s101, 0
	s_cselect_b32 s100, s100, 0
	s_or_b32 s101, s101, s100
.LBB0_255:
	ds_read_b128 v[146:149], v153
	ds_read_b128 v[160:163], v153 offset:1024
	ds_read_b128 v[164:167], v153 offset:2048
	ds_read_b128 v[168:171], v153 offset:3072
	s_add_u32 s64, s62, 0xfffc0080
	s_addc_u32 s65, s63, -1
	s_cmp_eq_u32 s94, 12
	s_cselect_b32 s67, s12, s65
	s_cselect_b32 s66, s53, s64
	s_cselect_b32 s65, s51, s93
	s_cselect_b32 s64, s59, s61
	v_lshl_add_u64 v[150:151], s[62:63], 0, v[142:143]
	s_add_i32 m0, s5, 0xc000
	ds_read_b128 v[172:175], v154
	ds_read_b128 v[176:179], v154 offset:1024
	ds_read_b128 v[180:183], v154 offset:2048
	ds_read_b128 v[184:187], v154 offset:3072
	ds_read_b128 v[188:191], v154 offset:4096
	ds_read_b128 v[192:195], v154 offset:5120
	ds_read_b128 v[196:199], v154 offset:6144
	ds_read_b128 v[200:203], v154 offset:7168
	global_load_lds_dwordx4 v[150:151], off
	v_lshl_add_u64 v[150:151], s[62:63], 0, v[144:145]
	s_add_i32 m0, s5, 0xe000
	s_nop 0
	global_load_lds_dwordx4 v[150:151], off
	s_waitcnt lgkmcnt(8)
	s_barrier
	s_waitcnt lgkmcnt(0)
	s_bitcmp1_b32 s101, 2
	s_cbranch_scc1 .Lskp1_0
	s_setprio 1
	s_waitcnt lgkmcnt(0)
	v_mfma_f32_16x16x32_bf16 v[124:127], v[146:149], v[172:175], v[124:127]
	v_mfma_f32_16x16x32_bf16 v[120:123], v[164:167], v[172:175], v[120:123]
	v_mfma_f32_16x16x32_bf16 v[108:111], v[146:149], v[180:183], v[108:111]
	v_mfma_f32_16x16x32_bf16 v[104:107], v[164:167], v[180:183], v[104:107]
	v_mfma_f32_16x16x32_bf16 v[92:95], v[146:149], v[188:191], v[92:95]
	v_mfma_f32_16x16x32_bf16 v[88:91], v[164:167], v[188:191], v[88:91]
	v_mfma_f32_16x16x32_bf16 v[76:79], v[146:149], v[196:199], v[76:79]
	v_mfma_f32_16x16x32_bf16 v[72:75], v[164:167], v[196:199], v[72:75]
	v_mfma_f32_16x16x32_bf16 v[124:127], v[160:163], v[176:179], v[124:127]
	v_mfma_f32_16x16x32_bf16 v[120:123], v[168:171], v[176:179], v[120:123]
	v_mfma_f32_16x16x32_bf16 v[108:111], v[160:163], v[184:187], v[108:111]
	v_mfma_f32_16x16x32_bf16 v[104:107], v[168:171], v[184:187], v[104:107]
	v_mfma_f32_16x16x32_bf16 v[92:95], v[160:163], v[192:195], v[92:95]
	v_mfma_f32_16x16x32_bf16 v[88:91], v[168:171], v[192:195], v[88:91]
	v_mfma_f32_16x16x32_bf16 v[76:79], v[160:163], v[200:203], v[76:79]
	v_mfma_f32_16x16x32_bf16 v[72:75], v[168:171], v[200:203], v[72:75]
	s_setprio 0
; #define PG8_STAGE(bufoff, gbase, voff) do { _Pragma("unroll") for (int _i = 0; _i < 2; ++_i) \
;         __builtin_amdgcn_global_load_lds((const unsigned*)((const char*)(gbase) + (voff)[_i]), (LAS unsigned*)(lds + (bufoff) + ldsw + _i * 8192), 16, 0, 0); } while (0)
; #define PG8_LDA(dst, b, h) do { _Pragma("unroll") for (int m = 0; m < 4; ++m) _Pragma("unroll") for (int k = 0; k < 2; ++k) dst[m][k] = *(const LAS bf16x8*)(lds + PG8_SA(b, h) + aoff + m * 2048 + k * 1024); } while (0)
; #define PG8_LDB(dst, b, h) do { _Pragma("unroll") for (int n = 0; n < 2; ++n) _Pragma("unroll") for (int k = 0; k < 2; ++k) dst[n][k] = *(const LAS bf16x8*)(lds + PG8_SB(b, h) + boff + n * 2048 + k * 1024); } while (0)
; #define PG8_MMA(ai, bj, At, Bt) do { __builtin_amdgcn_s_setprio(1); _Pragma("unroll") for (int m = 0; m < 4; ++m) _Pragma("unroll") for (int n = 0; n < 2; ++n) _Pragma("unroll") for (int k = 0; k < 2; ++k) \
;         acc[ai][bj][m][n] = __builtin_amdgcn_mfma_f32_16x16x32_bf16(Bt[n][k], At[m][k], acc[ai][bj][m][n], 0, 0, 0); __builtin_amdgcn_s_setprio(0); } while (0)
; #define PG8_WAIT_V(n) asm volatile("s_waitcnt vmcnt(" #n ")" ::: "memory")
; #define PG8_WAIT_L(n) asm volatile("s_waitcnt lgkmcnt(" #n ")" ::: "memory")
; #define PG8_BAR __builtin_amdgcn_s_barrier()
; #define PG8_SCHED __builtin_amdgcn_sched_barrier(0)
; template <class Epi, class Sched>
; __device__ __forceinline__ void gemm_phase(LAS unsigned char* lds, const int K, const Sched& S, const Epi& E) {
;     ...
;             PG8_WAIT_L(8); PG8_BAR; PG8_WAIT_L(0); PG8_MMA(0, 0, At, B0); PG8_BAR; PG8_SCHED;
;             PG8_LDB(B1, 0, 1); PG8_STAGE(PG8_SB(0, 0), b2, voffB);
;             PG8_BAR; PG8_WAIT_L(0); PG8_MMA(0, 1, At, B1); PG8_BAR;
;             PG8_LDA(At, 0, 1); PG8_STAGE(PG8_SA(0, 0), a2, voffA);
;             PG8_BAR; PG8_WAIT_L(0); PG8_MMA(1, 0, At, B0); PG8_BAR; PG8_SCHED;
;             PG8_STAGE(PG8_SB(0, 1), b2 + hstep, voffB);
;             PG8_WAIT_V(6); PG8_BAR; PG8_MMA(1, 1, At, B1); PG8_BAR;
.Lskp1_0:
	s_barrier
	s_add_i32 s95, s79, s4
	v_lshl_add_u64 v[150:151], s[64:65], 0, v[130:131]
	s_mov_b32 m0, s95
	ds_read_b128 v[204:207], v155
	ds_read_b128 v[208:211], v155 offset:1024
	ds_read_b128 v[212:215], v155 offset:2048
	ds_read_b128 v[216:219], v155 offset:3072
	global_load_lds_dwordx4 v[150:151], off
	v_lshl_add_u64 v[220:221], s[64:65], 0, v[134:135]
	s_add_i32 m0, s95, 0x2000
	s_nop 0
	global_load_lds_dwordx4 v[220:221], off
	s_barrier
	s_waitcnt lgkmcnt(0)
	s_bitcmp1_b32 s101, 0
	s_cbranch_scc1 .Lskp1_1
	s_setprio 1
	s_waitcnt lgkmcnt(0)
	v_mfma_f32_16x16x32_bf16 v[116:119], v[204:207], v[172:175], v[116:119]
	v_mfma_f32_16x16x32_bf16 v[112:115], v[212:215], v[172:175], v[112:115]
	v_mfma_f32_16x16x32_bf16 v[100:103], v[204:207], v[180:183], v[100:103]
	v_mfma_f32_16x16x32_bf16 v[96:99], v[212:215], v[180:183], v[96:99]
	v_mfma_f32_16x16x32_bf16 v[84:87], v[204:207], v[188:191], v[84:87]
	v_mfma_f32_16x16x32_bf16 v[80:83], v[212:215], v[188:191], v[80:83]
	v_mfma_f32_16x16x32_bf16 v[68:71], v[204:207], v[196:199], v[68:71]
	v_mfma_f32_16x16x32_bf16 v[64:67], v[212:215], v[196:199], v[64:67]
	v_mfma_f32_16x16x32_bf16 v[116:119], v[208:211], v[176:179], v[116:119]
	v_mfma_f32_16x16x32_bf16 v[112:115], v[216:219], v[176:179], v[112:115]
	v_mfma_f32_16x16x32_bf16 v[100:103], v[208:211], v[184:187], v[100:103]
	v_mfma_f32_16x16x32_bf16 v[96:99], v[216:219], v[184:187], v[96:99]
	v_mfma_f32_16x16x32_bf16 v[84:87], v[208:211], v[192:195], v[84:87]
	v_mfma_f32_16x16x32_bf16 v[80:83], v[216:219], v[192:195], v[80:83]
	v_mfma_f32_16x16x32_bf16 v[68:71], v[208:211], v[200:203], v[68:71]
	v_mfma_f32_16x16x32_bf16 v[64:67], v[216:219], v[200:203], v[64:67]
	s_setprio 0
.Lskp1_1:
	s_mov_b32 m0, s5
	v_lshl_add_u64 v[222:223], s[66:67], 0, v[128:129]
	s_barrier
	ds_read_b128 v[172:175], v154 offset:16384
	ds_read_b128 v[176:179], v154 offset:17408
	ds_read_b128 v[180:183], v154 offset:18432
	ds_read_b128 v[184:187], v154 offset:19456
	ds_read_b128 v[188:191], v154 offset:20480
	ds_read_b128 v[192:195], v154 offset:21504
	ds_read_b128 v[196:199], v154 offset:22528
	ds_read_b128 v[200:203], v154 offset:23552
	global_load_lds_dwordx4 v[222:223], off
	v_lshl_add_u64 v[224:225], s[66:67], 0, v[132:133]
	s_mov_b32 m0, s71
	s_nop 0
	global_load_lds_dwordx4 v[224:225], off
	s_barrier
	s_waitcnt lgkmcnt(0)
	s_and_b32 s100, s101, 6
	s_cbranch_scc1 .Lskp1_2
	s_setprio 1
	s_waitcnt lgkmcnt(0)
	v_mfma_f32_16x16x32_bf16 v[60:63], v[146:149], v[172:175], v[60:63]
	v_mfma_f32_16x16x32_bf16 v[56:59], v[164:167], v[172:175], v[56:59]
	v_mfma_f32_16x16x32_bf16 v[44:47], v[146:149], v[180:183], v[44:47]
	v_mfma_f32_16x16x32_bf16 v[40:43], v[164:167], v[180:183], v[40:43]
	v_mfma_f32_16x16x32_bf16 v[28:31], v[146:149], v[188:191], v[28:31]
	v_mfma_f32_16x16x32_bf16 v[24:27], v[164:167], v[188:191], v[24:27]
	v_mfma_f32_16x16x32_bf16 v[12:15], v[146:149], v[196:199], v[12:15]
	v_mfma_f32_16x16x32_bf16 v[8:11], v[164:167], v[196:199], v[8:11]
	v_mfma_f32_16x16x32_bf16 v[60:63], v[160:163], v[176:179], v[60:63]
	v_mfma_f32_16x16x32_bf16 v[56:59], v[168:171], v[176:179], v[56:59]
	v_mfma_f32_16x16x32_bf16 v[44:47], v[160:163], v[184:187], v[44:47]
	v_mfma_f32_16x16x32_bf16 v[40:43], v[168:171], v[184:187], v[40:43]
	v_mfma_f32_16x16x32_bf16 v[28:31], v[160:163], v[192:195], v[28:31]
	v_mfma_f32_16x16x32_bf16 v[24:27], v[168:171], v[192:195], v[24:27]
	v_mfma_f32_16x16x32_bf16 v[12:15], v[160:163], v[200:203], v[12:15]
	v_mfma_f32_16x16x32_bf16 v[8:11], v[168:171], v[200:203], v[8:11]
	s_setprio 0
.Lskp1_2:
	s_barrier
	s_add_u32 s96, s64, 0x40000
	s_addc_u32 s97, s65, 0
	s_add_i32 s95, s80, s4
	v_lshl_add_u64 v[146:147], s[96:97], 0, v[130:131]
	s_mov_b32 m0, s95
	s_nop 0
	global_load_lds_dwordx4 v[146:147], off
	v_lshl_add_u64 v[146:147], s[96:97], 0, v[134:135]
	s_add_i32 m0, s95, 0x2000
	s_nop 0
	global_load_lds_dwordx4 v[146:147], off
	s_waitcnt vmcnt(6)
	s_barrier
	s_and_b32 s100, s101, 3
	s_cbranch_scc1 .Lskp1_3
	s_setprio 1
	v_mfma_f32_16x16x32_bf16 v[52:55], v[204:207], v[172:175], v[52:55]
	v_mfma_f32_16x16x32_bf16 v[48:51], v[212:215], v[172:175], v[48:51]
	v_mfma_f32_16x16x32_bf16 v[36:39], v[204:207], v[180:183], v[36:39]
	v_mfma_f32_16x16x32_bf16 v[32:35], v[212:215], v[180:183], v[32:35]
	v_mfma_f32_16x16x32_bf16 v[20:23], v[204:207], v[188:191], v[20:23]
	v_mfma_f32_16x16x32_bf16 v[16:19], v[212:215], v[188:191], v[16:19]
	v_mfma_f32_16x16x32_bf16 v[4:7], v[204:207], v[196:199], v[4:7]
	v_mfma_f32_16x16x32_bf16 v[0:3], v[212:215], v[196:199], v[0:3]
	v_mfma_f32_16x16x32_bf16 v[52:55], v[208:211], v[176:179], v[52:55]
	v_mfma_f32_16x16x32_bf16 v[48:51], v[216:219], v[176:179], v[48:51]
	v_mfma_f32_16x16x32_bf16 v[36:39], v[208:211], v[184:187], v[36:39]
	v_mfma_f32_16x16x32_bf16 v[32:35], v[216:219], v[184:187], v[32:35]
	v_mfma_f32_16x16x32_bf16 v[20:23], v[208:211], v[192:195], v[20:23]
	v_mfma_f32_16x16x32_bf16 v[16:19], v[216:219], v[192:195], v[16:19]
	v_mfma_f32_16x16x32_bf16 v[4:7], v[208:211], v[200:203], v[4:7]
	v_mfma_f32_16x16x32_bf16 v[0:3], v[216:219], v[200:203], v[0:3]
	s_setprio 0
; #define PG8_STAGE(bufoff, gbase, voff) do { _Pragma("unroll") for (int _i = 0; _i < 2; ++_i) \
;         __builtin_amdgcn_global_load_lds((const unsigned*)((const char*)(gbase) + (voff)[_i]), (LAS unsigned*)(lds + (bufoff) + ldsw + _i * 8192), 16, 0, 0); } while (0)
; #define PG8_LDA(dst, b, h) do { _Pragma("unroll") for (int m = 0; m < 4; ++m) _Pragma("unroll") for (int k = 0; k < 2; ++k) dst[m][k] = *(const LAS bf16x8*)(lds + PG8_SA(b, h) + aoff + m * 2048 + k * 1024); } while (0)
; #define PG8_LDB(dst, b, h) do { _Pragma("unroll") for (int n = 0; n < 2; ++n) _Pragma("unroll") for (int k = 0; k < 2; ++k) dst[n][k] = *(const LAS bf16x8*)(lds + PG8_SB(b, h) + boff + n * 2048 + k * 1024); } while (0)
; #define PG8_MMA(ai, bj, At, Bt) do { __builtin_amdgcn_s_setprio(1); _Pragma("unroll") for (int m = 0; m < 4; ++m) _Pragma("unroll") for (int n = 0; n < 2; ++n) _Pragma("unroll") for (int k = 0; k < 2; ++k) \
;         acc[ai][bj][m][n] = __builtin_amdgcn_mfma_f32_16x16x32_bf16(Bt[n][k], At[m][k], acc[ai][bj][m][n], 0, 0, 0); __builtin_amdgcn_s_setprio(0); } while (0)
; #define PG8_WAIT_L(n) asm volatile("s_waitcnt lgkmcnt(" #n ")" ::: "memory")
; #define PG8_BAR __builtin_amdgcn_s_barrier()
; #define PG8_SCHED __builtin_amdgcn_sched_barrier(0)
; template <class Epi, class Sched>
; __device__ __forceinline__ void gemm_phase(LAS unsigned char* lds, const int K, const Sched& S, const Epi& E) {
;     ...
;             PG8_LDB(B0, 1, 0); PG8_SCHED; PG8_LDA(At, 1, 0); PG8_STAGE(PG8_SA(0, 1), a2 + hstep, voffA);
;             PG8_WAIT_L(8); PG8_BAR; PG8_WAIT_L(0); PG8_MMA(0, 0, At, B0); PG8_BAR; PG8_SCHED;
;             PG8_LDB(B1, 1, 1); PG8_STAGE(PG8_SB(1, 0), b3, voffB);
;             PG8_BAR; PG8_WAIT_L(0); PG8_MMA(0, 1, At, B1); PG8_BAR;
.Lskp1_3:
	s_add_i32 s95, 0, 0x18000
	v_add_u32_e32 v136, s95, v152
	s_barrier
	ds_read_b128 v[146:149], v136
	ds_read_b128 v[160:163], v136 offset:1024
	ds_read_b128 v[164:167], v136 offset:2048
	ds_read_b128 v[168:171], v136 offset:3072
	s_add_u32 s66, s66, 0x40000
	s_addc_u32 s67, s67, 0
	s_mov_b32 m0, s72
	v_lshl_add_u64 v[204:205], s[66:67], 0, v[128:129]
	ds_read_b128 v[172:175], v154 offset:32768
	ds_read_b128 v[176:179], v154 offset:33792
	ds_read_b128 v[180:183], v154 offset:34816
	ds_read_b128 v[184:187], v154 offset:35840
	ds_read_b128 v[188:191], v154 offset:36864
	ds_read_b128 v[192:195], v154 offset:37888
	ds_read_b128 v[196:199], v154 offset:38912
	ds_read_b128 v[200:203], v154 offset:39936
	global_load_lds_dwordx4 v[204:205], off
	v_lshl_add_u64 v[204:205], s[66:67], 0, v[132:133]
	s_mov_b32 m0, s73
	s_nop 0
	global_load_lds_dwordx4 v[204:205], off
	s_waitcnt lgkmcnt(8)
	s_barrier
	s_waitcnt lgkmcnt(0)
	s_bitcmp1_b32 s101, 2
	s_cbranch_scc1 .Lskp1_4
	s_setprio 1
	s_waitcnt lgkmcnt(0)
	v_mfma_f32_16x16x32_bf16 v[124:127], v[146:149], v[172:175], v[124:127]
	v_mfma_f32_16x16x32_bf16 v[120:123], v[164:167], v[172:175], v[120:123]
	v_mfma_f32_16x16x32_bf16 v[108:111], v[146:149], v[180:183], v[108:111]
	v_mfma_f32_16x16x32_bf16 v[104:107], v[164:167], v[180:183], v[104:107]
	v_mfma_f32_16x16x32_bf16 v[92:95], v[146:149], v[188:191], v[92:95]
	v_mfma_f32_16x16x32_bf16 v[88:91], v[164:167], v[188:191], v[88:91]
	v_mfma_f32_16x16x32_bf16 v[76:79], v[146:149], v[196:199], v[76:79]
	v_mfma_f32_16x16x32_bf16 v[72:75], v[164:167], v[196:199], v[72:75]
	v_mfma_f32_16x16x32_bf16 v[124:127], v[160:163], v[176:179], v[124:127]
	v_mfma_f32_16x16x32_bf16 v[120:123], v[168:171], v[176:179], v[120:123]
	v_mfma_f32_16x16x32_bf16 v[108:111], v[160:163], v[184:187], v[108:111]
	v_mfma_f32_16x16x32_bf16 v[104:107], v[168:171], v[184:187], v[104:107]
	v_mfma_f32_16x16x32_bf16 v[92:95], v[160:163], v[192:195], v[92:95]
	v_mfma_f32_16x16x32_bf16 v[88:91], v[168:171], v[192:195], v[88:91]
	v_mfma_f32_16x16x32_bf16 v[76:79], v[160:163], v[200:203], v[76:79]
	v_mfma_f32_16x16x32_bf16 v[72:75], v[168:171], v[200:203], v[72:75]
	s_setprio 0
.Lskp1_4:
	s_barrier
	s_add_i32 s66, 0, 0x1c000
	s_add_i32 s67, s95, s4
	v_add_u32_e32 v136, s66, v152
	v_lshl_add_u64 v[150:151], v[150:151], 0, s[14:15]
	s_mov_b32 m0, s67
	ds_read_b128 v[204:207], v136
	ds_read_b128 v[208:211], v136 offset:1024
	ds_read_b128 v[212:215], v136 offset:2048
	ds_read_b128 v[216:219], v136 offset:3072
	global_load_lds_dwordx4 v[150:151], off
	v_lshl_add_u64 v[150:151], v[220:221], 0, s[14:15]
	s_add_i32 m0, s67, 0x2000
	s_nop 0
	global_load_lds_dwordx4 v[150:151], off
	s_barrier
	s_waitcnt lgkmcnt(0)
	s_bitcmp1_b32 s101, 0
	s_cbranch_scc1 .Lskp1_5
	s_setprio 1
	s_waitcnt lgkmcnt(0)
	v_mfma_f32_16x16x32_bf16 v[116:119], v[204:207], v[172:175], v[116:119]
	v_mfma_f32_16x16x32_bf16 v[112:115], v[212:215], v[172:175], v[112:115]
	v_mfma_f32_16x16x32_bf16 v[100:103], v[204:207], v[180:183], v[100:103]
	v_mfma_f32_16x16x32_bf16 v[96:99], v[212:215], v[180:183], v[96:99]
	v_mfma_f32_16x16x32_bf16 v[84:87], v[204:207], v[188:191], v[84:87]
	v_mfma_f32_16x16x32_bf16 v[80:83], v[212:215], v[188:191], v[80:83]
	v_mfma_f32_16x16x32_bf16 v[68:71], v[204:207], v[196:199], v[68:71]
	v_mfma_f32_16x16x32_bf16 v[64:67], v[212:215], v[196:199], v[64:67]
	v_mfma_f32_16x16x32_bf16 v[116:119], v[208:211], v[176:179], v[116:119]
	v_mfma_f32_16x16x32_bf16 v[112:115], v[216:219], v[176:179], v[112:115]
	v_mfma_f32_16x16x32_bf16 v[100:103], v[208:211], v[184:187], v[100:103]
	v_mfma_f32_16x16x32_bf16 v[96:99], v[216:219], v[184:187], v[96:99]
	v_mfma_f32_16x16x32_bf16 v[84:87], v[208:211], v[192:195], v[84:87]
	v_mfma_f32_16x16x32_bf16 v[80:83], v[216:219], v[192:195], v[80:83]
	v_mfma_f32_16x16x32_bf16 v[68:71], v[208:211], v[200:203], v[68:71]
	v_mfma_f32_16x16x32_bf16 v[64:67], v[216:219], v[200:203], v[64:67]
	s_setprio 0
; #define PG8_STAGE(bufoff, gbase, voff) do { _Pragma("unroll") for (int _i = 0; _i < 2; ++_i) \
;         __builtin_amdgcn_global_load_lds((const unsigned*)((const char*)(gbase) + (voff)[_i]), (LAS unsigned*)(lds + (bufoff) + ldsw + _i * 8192), 16, 0, 0); } while (0)
; #define PG8_LDA(dst, b, h) do { _Pragma("unroll") for (int m = 0; m < 4; ++m) _Pragma("unroll") for (int k = 0; k < 2; ++k) dst[m][k] = *(const LAS bf16x8*)(lds + PG8_SA(b, h) + aoff + m * 2048 + k * 1024); } while (0)
; #define PG8_MMA(ai, bj, At, Bt) do { __builtin_amdgcn_s_setprio(1); _Pragma("unroll") for (int m = 0; m < 4; ++m) _Pragma("unroll") for (int n = 0; n < 2; ++n) _Pragma("unroll") for (int k = 0; k < 2; ++k) \
;         acc[ai][bj][m][n] = __builtin_amdgcn_mfma_f32_16x16x32_bf16(Bt[n][k], At[m][k], acc[ai][bj][m][n], 0, 0, 0); __builtin_amdgcn_s_setprio(0); } while (0)
; #define PG8_WAIT_V(n) asm volatile("s_waitcnt vmcnt(" #n ")" ::: "memory")
; #define PG8_WAIT_L(n) asm volatile("s_waitcnt lgkmcnt(" #n ")" ::: "memory")
; #define PG8_BAR __builtin_amdgcn_s_barrier()
; #define PG8_SCHED __builtin_amdgcn_sched_barrier(0)
; template <class Epi, class Sched>
; __device__ __forceinline__ void gemm_phase(LAS unsigned char* lds, const int K, const Sched& S, const Epi& E) {
;     ...
;             PG8_LDA(At, 1, 1); PG8_STAGE(PG8_SA(1, 0), a3, voffA);
;             PG8_BAR; PG8_WAIT_L(0); PG8_MMA(1, 0, At, B0); PG8_BAR; PG8_SCHED;
;             PG8_STAGE(PG8_SB(1, 1), b3 + hstep, voffB);
;             PG8_WAIT_V(6); PG8_BAR; PG8_MMA(1, 1, At, B1); PG8_BAR;
.Lskp1_5:
	s_mov_b32 m0, s77
	v_lshl_add_u64 v[150:151], v[222:223], 0, s[14:15]
	s_barrier
	ds_read_b128 v[172:175], v154 offset:49152
	ds_read_b128 v[176:179], v154 offset:50176
	ds_read_b128 v[180:183], v154 offset:51200
	ds_read_b128 v[184:187], v154 offset:52224
	ds_read_b128 v[188:191], v154 offset:53248
	ds_read_b128 v[192:195], v154 offset:54272
	ds_read_b128 v[196:199], v154 offset:55296
	ds_read_b128 v[200:203], v154 offset:56320
	global_load_lds_dwordx4 v[150:151], off
	v_lshl_add_u64 v[150:151], v[224:225], 0, s[14:15]
	s_mov_b32 m0, s78
	s_nop 0
	global_load_lds_dwordx4 v[150:151], off
	s_barrier
	s_waitcnt lgkmcnt(0)
	s_and_b32 s100, s101, 6
	s_cbranch_scc1 .Lskp1_6
	s_setprio 1
	s_waitcnt lgkmcnt(0)
	v_mfma_f32_16x16x32_bf16 v[60:63], v[146:149], v[172:175], v[60:63]
	v_mfma_f32_16x16x32_bf16 v[56:59], v[164:167], v[172:175], v[56:59]
	v_mfma_f32_16x16x32_bf16 v[44:47], v[146:149], v[180:183], v[44:47]
	v_mfma_f32_16x16x32_bf16 v[40:43], v[164:167], v[180:183], v[40:43]
	v_mfma_f32_16x16x32_bf16 v[28:31], v[146:149], v[188:191], v[28:31]
	v_mfma_f32_16x16x32_bf16 v[24:27], v[164:167], v[188:191], v[24:27]
	v_mfma_f32_16x16x32_bf16 v[12:15], v[146:149], v[196:199], v[12:15]
	v_mfma_f32_16x16x32_bf16 v[8:11], v[164:167], v[196:199], v[8:11]
	v_mfma_f32_16x16x32_bf16 v[60:63], v[160:163], v[176:179], v[60:63]
	v_mfma_f32_16x16x32_bf16 v[56:59], v[168:171], v[176:179], v[56:59]
	v_mfma_f32_16x16x32_bf16 v[44:47], v[160:163], v[184:187], v[44:47]
	v_mfma_f32_16x16x32_bf16 v[40:43], v[168:171], v[184:187], v[40:43]
	v_mfma_f32_16x16x32_bf16 v[28:31], v[160:163], v[192:195], v[28:31]
	v_mfma_f32_16x16x32_bf16 v[24:27], v[168:171], v[192:195], v[24:27]
	v_mfma_f32_16x16x32_bf16 v[12:15], v[160:163], v[200:203], v[12:15]
	v_mfma_f32_16x16x32_bf16 v[8:11], v[168:171], v[200:203], v[8:11]
	s_setprio 0
.Lskp1_6:
	s_barrier
	s_add_u32 s64, s64, 0x40080
	s_addc_u32 s65, s65, 0
	s_add_i32 s66, s66, s4
	v_lshl_add_u64 v[146:147], s[64:65], 0, v[130:131]
	s_mov_b32 m0, s66
	s_nop 0
	global_load_lds_dwordx4 v[146:147], off
	v_lshl_add_u64 v[146:147], s[64:65], 0, v[134:135]
	s_add_i32 m0, s66, 0x2000
	s_nop 0
	global_load_lds_dwordx4 v[146:147], off
	s_waitcnt vmcnt(6)
	s_barrier
	s_and_b32 s100, s101, 3
	s_cbranch_scc1 .Lskp1_7
	s_setprio 1
	v_mfma_f32_16x16x32_bf16 v[52:55], v[204:207], v[172:175], v[52:55]
	v_mfma_f32_16x16x32_bf16 v[48:51], v[212:215], v[172:175], v[48:51]
	v_mfma_f32_16x16x32_bf16 v[36:39], v[204:207], v[180:183], v[36:39]
	v_mfma_f32_16x16x32_bf16 v[32:35], v[212:215], v[180:183], v[32:35]
	v_mfma_f32_16x16x32_bf16 v[20:23], v[204:207], v[188:191], v[20:23]
	v_mfma_f32_16x16x32_bf16 v[16:19], v[212:215], v[188:191], v[16:19]
	v_mfma_f32_16x16x32_bf16 v[4:7], v[204:207], v[196:199], v[4:7]
	v_mfma_f32_16x16x32_bf16 v[0:3], v[212:215], v[196:199], v[0:3]
	v_mfma_f32_16x16x32_bf16 v[52:55], v[208:211], v[176:179], v[52:55]
	v_mfma_f32_16x16x32_bf16 v[48:51], v[216:219], v[176:179], v[48:51]
	v_mfma_f32_16x16x32_bf16 v[36:39], v[208:211], v[184:187], v[36:39]
	v_mfma_f32_16x16x32_bf16 v[32:35], v[216:219], v[184:187], v[32:35]
	v_mfma_f32_16x16x32_bf16 v[20:23], v[208:211], v[192:195], v[20:23]
	v_mfma_f32_16x16x32_bf16 v[16:19], v[216:219], v[192:195], v[16:19]
	v_mfma_f32_16x16x32_bf16 v[4:7], v[208:211], v[200:203], v[4:7]
	v_mfma_f32_16x16x32_bf16 v[0:3], v[216:219], v[200:203], v[0:3]
	s_setprio 0

; template <bool NOMAX>
; __device__ __forceinline__ void attn_block(const Params& P, LAS unsigned char* lds, int qR0, int h, int kR0, int kR1, int ntiles, int jmax, int nlast, int qvalid) {
;     ...
;     for (int j = 0; j < ntiles; ++j) {
;         const int buf = j & 1;
;         if (j + 1 < ntiles) { const int Rn = (kR1 >= 0 && j + 1 >= 16) ? kR1 : kR0 + 64 * (j + 1);
;             attn_stage_issue(P, lds, st, Rn, buf ^ 1, tid); }
;         if (j <= jmax) {
;             const LAS unsigned char* kb = lds + L_K0 + buf * KBUF + r * 384; const LAS unsigned char* vb = lds + L_V0 + buf * VBUF + r * 128;
;             const LAS unsigned char* rkb = lds + L_RKT + j * 256 + 16 * hh;
;             f32x16 sacc[2];
; #pragma unroll
;             for (int kt = 0; kt < 2; ++kt) {
; #pragma unroll
;                 for (int e = 0; e < 16; ++e) sacc[kt][e] = 0.f;
; #pragma unroll
;                 for (int s = 0; s < 12; ++s) { const bf16x8 kf = *(const LAS bf16x8*)(kb + kt * (32 * 384) + (s >> 2) * 128 + oc[s & 3]); sacc[kt] = mfma32(kf, qf[s], sacc[kt]); }
;             }
; #pragma unroll
;             for (int kt = 0; kt < 2; ++kt)
; #pragma unroll
;                 for (int gq = 0; gq < 4; ++gq) { const f32x4 rk4 = *(const LAS f32x4*)(rkb + (32 * kt + 8 * gq) * 4);
; #pragma unroll
;                     for (int i = 0; i < 4; ++i) sacc[kt][4 * gq + i] *= rk4[i]; }
;             if (j == ntiles - 1 && nlast < 64) {
; #pragma unroll
;                 for (int kt = 0; kt < 2; ++kt)
; #pragma unroll
;                     for (int e = 0; e < 16; ++e) { const int key = 32 * kt + (e & 3) + 8 * (e >> 2) + 4 * hh; if (key >= nlast) sacc[kt][e] = -1e30f; } }
;             float mnew = 0.f;
;             if constexpr (!NOMAX) {
;                 float mx = sacc[0][0];
; #pragma unroll
;                 for (int kt = 0; kt < 2; ++kt)
; #pragma unroll
;                     for (int e = 0; e < 16; ++e) mx = fmaxf(mx, sacc[kt][e]);
;                 mx = fmaxf(mx, __shfl_xor(mx, 32));
;                 const float mcand = fmaxf(mrun, mx);
;                 if (__any(mcand > mrun + 8.0f)) { const float alpha = __builtin_amdgcn_exp2f(mrun - mcand); lrun *= alpha;
; #pragma unroll
;                     for (int dt = 0; dt < 4; ++dt)
; #pragma unroll
;                         for (int e = 0; e < 16; ++e) oacc[dt][e] *= alpha;
;                     mrun = mcand; }
.Lattn_tail_b:
	s_waitcnt vmcnt(0)
	s_addk_i32 s15, 0x100
	s_add_i32 s14, s14, 1
	v_add_u32_e32 v180, 0x80, v180
	v_add_u32_e32 v181, 0x80, v181
	s_cmp_eq_u32 s15, 0
	v_add_u32_e32 v161, 64, v161
	s_waitcnt vmcnt(0) lgkmcnt(0)
	s_barrier
	s_cbranch_scc1 .LBB0_989
.LBB0_987:
	s_and_b32 s34, s14, 1
	s_xor_b32 s12, s34, 1
	v_readfirstlane_b32 s13, v168
	s_ashr_i32 s13, s13, 6
	s_mul_i32 s35, s12, 0x6000
	s_mul_i32 s39, s13, 0xc00
	s_add_i32 s39, s35, s39
	s_lshl_b32 s12, s12, 14
	s_lshl_b32 s13, s13, 11
	s_add_i32 s60, s12, s13
	s_add_i32 s60, s60, 0xc000
	v_cmp_le_i32_e32 vcc, s14, v155
	s_cbranch_vccz .Lattn_inact_b
	s_mul_i32 s35, s34, 0x6000
	v_add_u32_e32 v253, s35, v178
	v_add_u32_e32 v214, v253, v167
	v_add_u32_e32 v215, v253, v165
	v_add_u32_e32 v216, v253, v166
	v_add_u32_e32 v217, v253, v163
	ds_read_b128 v[182:185], v214
	ds_read_b128 v[186:189], v215
	ds_read_b128 v[190:193], v216
	ds_read_b128 v[194:197], v217
	ds_read_b128 v[198:201], v214 offset:128
	ds_read_b128 v[202:205], v215 offset:128
	v_lshl_add_u32 v254, v161, v175, v169
	s_mov_b32 m0, s39
	s_nop 0
	global_load_lds_dwordx4 v254, s[18:19]
	v_lshl_add_u32 v254, v161, v176, v171
	s_add_i32 m0, s39, 0x400
	s_nop 0
	global_load_lds_dwordx4 v254, s[18:19]
	v_lshl_add_u32 v254, v161, v177, v172
	s_add_i32 m0, s39, 0x800
	s_nop 0
	global_load_lds_dwordx4 v254, s[18:19]
	s_waitcnt lgkmcnt(5)
	v_mfma_f32_32x32x16_bf16 v[64:79], v[182:185], v[100:103], 0
	ds_read_b128 v[206:209], v216 offset:128
	s_mov_b32 m0, s60
	s_nop 0
	global_load_lds_dwordx4 v181, s[18:19]
	v_add_u32_e32 v219, s15, v179
	s_waitcnt lgkmcnt(5)
	v_mfma_f32_32x32x16_bf16 v[64:79], v[186:189], v[104:107], v[64:79]
	ds_read_b128 v[210:213], v217 offset:128
	s_add_i32 m0, s60, 0x400
	s_nop 0
	global_load_lds_dwordx4 v180, s[18:19]
	v_add_u32_e32 v219, 0x14f00, v219
	s_waitcnt lgkmcnt(5)
	v_mfma_f32_32x32x16_bf16 v[64:79], v[190:193], v[108:111], v[64:79]
	ds_read_b128 v[182:185], v214 offset:256
	v_lshl_add_u32 v218, s34, 14, v170
	s_waitcnt lgkmcnt(5)
	v_mfma_f32_32x32x16_bf16 v[64:79], v[194:197], v[112:115], v[64:79]
	ds_read_b128 v[186:189], v215 offset:256
	v_sub_u32_e32 v218, v218, v253
	s_waitcnt lgkmcnt(5)
	v_mfma_f32_32x32x16_bf16 v[64:79], v[198:201], v[116:119], v[64:79]
	ds_read_b128 v[190:193], v216 offset:256
	s_waitcnt lgkmcnt(5)
	v_mfma_f32_32x32x16_bf16 v[64:79], v[202:205], v[120:123], v[64:79]
	ds_read_b128 v[194:197], v217 offset:256
	s_waitcnt lgkmcnt(5)
	v_mfma_f32_32x32x16_bf16 v[64:79], v[206:209], v[124:127], v[64:79]
	ds_read_b128 v[198:201], v214 offset:12288
	s_waitcnt lgkmcnt(5)
	v_mfma_f32_32x32x16_bf16 v[64:79], v[210:213], v[132:135], v[64:79]
	ds_read_b128 v[202:205], v215 offset:12288
	s_waitcnt lgkmcnt(5)
	v_mfma_f32_32x32x16_bf16 v[64:79], v[182:185], v[136:139], v[64:79]
	ds_read_b128 v[206:209], v216 offset:12288
	s_waitcnt lgkmcnt(5)
	v_mfma_f32_32x32x16_bf16 v[64:79], v[186:189], v[140:143], v[64:79]
	ds_read_b128 v[210:213], v217 offset:12288
	ds_read_b128 v[232:235], v219
	s_waitcnt lgkmcnt(6)
	v_mfma_f32_32x32x16_bf16 v[64:79], v[190:193], v[144:147], v[64:79]
	ds_read_b128 v[182:185], v214 offset:12416
	ds_read_b128 v[236:239], v219 offset:32
	s_waitcnt lgkmcnt(7)
	v_mfma_f32_32x32x16_bf16 v[64:79], v[194:197], v[128:131], v[64:79]
	ds_read_b128 v[186:189], v215 offset:12416
	ds_read_b128 v[240:243], v219 offset:64
	s_waitcnt lgkmcnt(8)
	v_mfma_f32_32x32x16_bf16 v[80:95], v[198:201], v[100:103], 0
	ds_read_b128 v[190:193], v216 offset:12416
	ds_read_b128 v[244:247], v219 offset:96
	s_waitcnt lgkmcnt(9)
	v_mfma_f32_32x32x16_bf16 v[80:95], v[202:205], v[104:107], v[80:95]
	ds_read_b128 v[194:197], v217 offset:12416
	s_waitcnt lgkmcnt(9)
	v_mfma_f32_32x32x16_bf16 v[80:95], v[206:209], v[108:111], v[80:95]
	ds_read_b128 v[198:201], v214 offset:12544
	s_waitcnt lgkmcnt(9)
	v_mfma_f32_32x32x16_bf16 v[80:95], v[210:213], v[112:115], v[80:95]
	ds_read_b128 v[202:205], v215 offset:12544
	s_waitcnt lgkmcnt(9)
	v_mul_f32_e32 v64, v64, v232
	v_mul_f32_e32 v65, v65, v233
	v_mul_f32_e32 v66, v66, v234
	v_mul_f32_e32 v67, v67, v235
	v_exp_f32_e32 v64, v64
	s_waitcnt lgkmcnt(8)
	v_mfma_f32_32x32x16_bf16 v[80:95], v[182:185], v[116:119], v[80:95]
	ds_read_b128 v[206:209], v216 offset:12544
	s_waitcnt lgkmcnt(8)
	v_mul_f32_e32 v68, v68, v236
	v_exp_f32_e32 v65, v65
	v_mul_f32_e32 v69, v69, v237
	v_exp_f32_e32 v66, v66
	v_mul_f32_e32 v70, v70, v238
	s_waitcnt lgkmcnt(7)
	v_mfma_f32_32x32x16_bf16 v[80:95], v[186:189], v[120:123], v[80:95]
	ds_read_b128 v[210:213], v217 offset:12544
	v_exp_f32_e32 v67, v67
	v_mul_f32_e32 v71, v71, v239
	v_add_u32_e32 v214, v214, v218
	v_add_u32_e32 v215, v215, v218
	v_add_u32_e32 v216, v216, v218
	v_add_u32_e32 v217, v217, v218
	s_waitcnt lgkmcnt(6)
	v_mfma_f32_32x32x16_bf16 v[80:95], v[190:193], v[124:127], v[80:95]
	ds_read_b128 v[182:185], v214 offset:49152
	v_exp_f32_e32 v68, v68
	v_cvt_pk_bf16_f32 v222, v64, v65
	v_exp_f32_e32 v69, v69
	v_cvt_pk_bf16_f32 v223, v66, v67
	v_exp_f32_e32 v70, v70
	s_waitcnt lgkmcnt(5)
	v_mfma_f32_32x32x16_bf16 v[80:95], v[194:197], v[132:135], v[80:95]
	ds_read_b128 v[186:189], v214 offset:53248
	v_exp_f32_e32 v71, v71
	v_cvt_pk_bf16_f32 v224, v68, v69
	v_cvt_pk_bf16_f32 v225, v70, v71
	v_mul_f32_e32 v72, v72, v240
	v_mul_f32_e32 v73, v73, v241
	s_waitcnt lgkmcnt(5)
	v_mfma_f32_32x32x16_bf16 v[80:95], v[198:201], v[136:139], v[80:95]
	ds_read_b128 v[190:193], v214 offset:57344
	v_mul_f32_e32 v74, v74, v242
	v_mul_f32_e32 v75, v75, v243
	v_exp_f32_e32 v72, v72
	v_mul_f32_e32 v76, v76, v244
	v_exp_f32_e32 v73, v73
	s_waitcnt lgkmcnt(5)
; #define LAS __attribute__((address_space(3)))
; __device__ __forceinline__ f32x16 mfma32(bf16x8 a, bf16x8 b, f32x16 c) { return __builtin_amdgcn_mfma_f32_32x32x16_bf16(a, b, c, 0, 0, 0); }
; __device__ __forceinline__ void attn_stage_issue(const Params& P, LAS unsigned char* lds, const AttnStage& st, int R0, int buf, int tid) {
;     ...
;     for (int i = 0; i < 3; ++i) __builtin_amdgcn_global_load_lds((const unsigned*)(ws + (st.kofs[i] + (unsigned)R0 * st.kstr[i])), (LAS unsigned*)(lds + L_K0 + buf * KBUF + (w * 3 + i) * 1024), 16, 0, 0);
; #pragma unroll
;     for (int i = 0; i < 2; ++i) __builtin_amdgcn_global_load_lds((const unsigned*)(ws + (st.vofs[i] + (unsigned)R0 * 2u)), (LAS unsigned*)(lds + L_V0 + buf * VBUF + (w * 2 + i) * 1024), 16, 0, 0);
; template <bool NOMAX>
; __device__ __forceinline__ void attn_block(const Params& P, LAS unsigned char* lds, int qR0, int h, int kR0, int kR1, int ntiles, int jmax, int nlast, int qvalid) {
;     ...
;             for (int kt = 0; kt < 2; ++kt)
; #pragma unroll
;                 for (int e = 0; e < 16; ++e) { const float p = __builtin_amdgcn_exp2f(NOMAX ? sacc[kt][e] : sacc[kt][e] - mnew); sacc[kt][e] = p; ps += p; }
;             lrun += ps;
;             bf16x8 pf[2][2];
; #pragma unroll
;             for (int kt = 0; kt < 2; ++kt)
; #pragma unroll
;                 for (int s2 = 0; s2 < 2; ++s2) { u32x4 v; v.x = pk2(sacc[kt][8 * s2 + 0], sacc[kt][8 * s2 + 1]); v.y = pk2(sacc[kt][8 * s2 + 2], sacc[kt][8 * s2 + 3]); v.z = pk2(sacc[kt][8 * s2 + 4], sacc[kt][8 * s2 + 5]); v.w = pk2(sacc[kt][8 * s2 + 6], sacc[kt][8 * s2 + 7]); pf[kt][s2] = *(const bf16x8*)&v; }
; #pragma unroll
;             for (int dt = 0; dt < 4; ++dt)
; #pragma unroll
;                 for (int kt = 0; kt < 2; ++kt)
; #pragma unroll
;                     for (int s2 = 0; s2 < 2; ++s2) { const bf16x8 vf = *(const LAS bf16x8*)(vb + dt * (32 * 128) + oc[2 * kt + s2]);
;                         oacc[dt] = mfma32(vf, pf[kt][s2], oacc[dt]); }
;         }
;         asm volatile("s_waitcnt vmcnt(0)" ::: "memory");
;         __syncthreads();
	v_mfma_f32_32x32x16_bf16 v[80:95], v[202:205], v[140:143], v[80:95]
	ds_read_b128 v[194:197], v214 offset:61440
	v_mul_f32_e32 v77, v77, v245
	v_exp_f32_e32 v74, v74
	v_mul_f32_e32 v78, v78, v246
	v_exp_f32_e32 v75, v75
	v_mul_f32_e32 v79, v79, v247
	s_waitcnt lgkmcnt(5)
	v_mfma_f32_32x32x16_bf16 v[80:95], v[206:209], v[144:147], v[80:95]
	ds_read_b128 v[198:201], v215 offset:49152
	v_exp_f32_e32 v76, v76
	v_cvt_pk_bf16_f32 v226, v72, v73
	v_exp_f32_e32 v77, v77
	v_cvt_pk_bf16_f32 v227, v74, v75
	ds_read_b128 v[232:235], v219 offset:128
	ds_read_b128 v[236:239], v219 offset:160
	s_waitcnt lgkmcnt(7)
	v_mfma_f32_32x32x16_bf16 v[80:95], v[210:213], v[128:131], v[80:95]
	ds_read_b128 v[202:205], v215 offset:53248
	v_exp_f32_e32 v78, v78
	v_exp_f32_e32 v79, v79
	v_cvt_pk_bf16_f32 v228, v76, v77
	v_cvt_pk_bf16_f32 v229, v78, v79
	ds_read_b128 v[240:243], v219 offset:192
	ds_read_b128 v[244:247], v219 offset:224
	s_waitcnt lgkmcnt(9)
	v_mfma_f32_32x32x16_bf16 v[48:63], v[182:185], v[222:225], v[48:63]
	ds_read_b128 v[206:209], v215 offset:57344
	v_add_f32_e32 v231, v64, v65
	v_add_f32_e32 v231, v66, v231
	v_add_f32_e32 v231, v67, v231
	v_add_f32_e32 v231, v68, v231
	s_waitcnt lgkmcnt(9)
	v_mfma_f32_32x32x16_bf16 v[32:47], v[186:189], v[222:225], v[32:47]
	ds_read_b128 v[210:213], v215 offset:61440
	v_add_f32_e32 v231, v69, v231
	v_add_f32_e32 v231, v70, v231
	v_add_f32_e32 v231, v71, v231
	v_add_f32_e32 v231, v72, v231
	s_waitcnt lgkmcnt(9)
	v_mfma_f32_32x32x16_bf16 v[16:31], v[190:193], v[222:225], v[16:31]
	ds_read_b128 v[182:185], v216 offset:49152
	v_add_f32_e32 v231, v73, v231
	v_add_f32_e32 v231, v74, v231
	v_add_f32_e32 v231, v75, v231
	v_add_f32_e32 v231, v76, v231
	s_waitcnt lgkmcnt(9)
	v_mfma_f32_32x32x16_bf16 v[0:15], v[194:197], v[222:225], v[0:15]
	ds_read_b128 v[186:189], v216 offset:53248
	s_waitcnt lgkmcnt(8)
	v_mul_f32_e32 v80, v80, v232
	v_mul_f32_e32 v81, v81, v233
	v_mul_f32_e32 v82, v82, v234
	v_mul_f32_e32 v83, v83, v235
	v_mfma_f32_32x32x16_bf16 v[48:63], v[198:201], v[226:229], v[48:63]
	ds_read_b128 v[190:193], v216 offset:57344
	v_exp_f32_e32 v80, v80
	s_waitcnt lgkmcnt(8)
	v_mul_f32_e32 v84, v84, v236
	v_exp_f32_e32 v81, v81
	v_mul_f32_e32 v85, v85, v237
	s_waitcnt lgkmcnt(7)
	v_mfma_f32_32x32x16_bf16 v[32:47], v[202:205], v[226:229], v[32:47]
	ds_read_b128 v[194:197], v216 offset:61440
	v_exp_f32_e32 v82, v82
	v_mul_f32_e32 v86, v86, v238
	v_exp_f32_e32 v83, v83
	v_mul_f32_e32 v87, v87, v239
	s_waitcnt lgkmcnt(5)
	v_mfma_f32_32x32x16_bf16 v[16:31], v[206:209], v[226:229], v[16:31]
	ds_read_b128 v[198:201], v217 offset:49152
	v_exp_f32_e32 v84, v84
	v_cvt_pk_bf16_f32 v248, v80, v81
	v_exp_f32_e32 v85, v85
	v_cvt_pk_bf16_f32 v249, v82, v83
	s_waitcnt lgkmcnt(5)
	v_mfma_f32_32x32x16_bf16 v[0:15], v[210:213], v[226:229], v[0:15]
	ds_read_b128 v[202:205], v217 offset:53248
	v_exp_f32_e32 v86, v86
	v_exp_f32_e32 v87, v87
	v_cvt_pk_bf16_f32 v250, v84, v85
	v_cvt_pk_bf16_f32 v251, v86, v87
	v_add_f32_e32 v231, v77, v231
	v_add_f32_e32 v231, v78, v231
	v_add_f32_e32 v231, v79, v231
	s_waitcnt lgkmcnt(5)
	v_mfma_f32_32x32x16_bf16 v[48:63], v[182:185], v[248:251], v[48:63]
	ds_read_b128 v[206:209], v217 offset:57344
	v_mul_f32_e32 v88, v88, v240
	v_mul_f32_e32 v89, v89, v241
	v_mul_f32_e32 v90, v90, v242
	v_mul_f32_e32 v91, v91, v243
	v_exp_f32_e32 v88, v88
	s_waitcnt lgkmcnt(5)
	v_mfma_f32_32x32x16_bf16 v[32:47], v[186:189], v[248:251], v[32:47]
	ds_read_b128 v[210:213], v217 offset:61440
	v_mul_f32_e32 v92, v92, v244
	v_exp_f32_e32 v89, v89
	v_mul_f32_e32 v93, v93, v245
	v_exp_f32_e32 v90, v90
	v_mul_f32_e32 v94, v94, v246
	s_waitcnt lgkmcnt(5)
	v_mfma_f32_32x32x16_bf16 v[16:31], v[190:193], v[248:251], v[16:31]
	v_exp_f32_e32 v91, v91
	v_mul_f32_e32 v95, v95, v247
	v_exp_f32_e32 v92, v92
	v_cvt_pk_bf16_f32 v64, v88, v89
	v_exp_f32_e32 v93, v93
	s_waitcnt lgkmcnt(4)
	v_mfma_f32_32x32x16_bf16 v[0:15], v[194:197], v[248:251], v[0:15]
	v_cvt_pk_bf16_f32 v65, v90, v91
	v_exp_f32_e32 v94, v94
	v_exp_f32_e32 v95, v95
	v_cvt_pk_bf16_f32 v66, v92, v93
	v_cvt_pk_bf16_f32 v67, v94, v95
	v_add_f32_e32 v252, v80, v81
	v_add_f32_e32 v252, v82, v252
	s_waitcnt lgkmcnt(3)
	v_mfma_f32_32x32x16_bf16 v[48:63], v[198:201], v[64:67], v[48:63]
	v_add_f32_e32 v252, v83, v252
	v_add_f32_e32 v252, v84, v252
	v_add_f32_e32 v252, v85, v252
	v_add_f32_e32 v252, v86, v252
	s_waitcnt lgkmcnt(2)
	v_mfma_f32_32x32x16_bf16 v[32:47], v[202:205], v[64:67], v[32:47]
	v_add_f32_e32 v252, v87, v252
	v_add_f32_e32 v252, v88, v252
	v_add_f32_e32 v252, v89, v252
	v_add_f32_e32 v252, v90, v252
	s_waitcnt lgkmcnt(1)
	v_mfma_f32_32x32x16_bf16 v[16:31], v[206:209], v[64:67], v[16:31]
	v_add_f32_e32 v252, v91, v252
	v_add_f32_e32 v252, v92, v252
	v_add_f32_e32 v252, v93, v252
	v_add_f32_e32 v252, v94, v252
	s_waitcnt lgkmcnt(0)
	v_mfma_f32_32x32x16_bf16 v[0:15], v[210:213], v[64:67], v[0:15]
	v_add_f32_e32 v252, v95, v252
	v_add_f32_e32 v231, v231, v252
	v_add_f32_e32 v162, v162, v231
	s_branch .Lattn_tail_b
.Lattn_inact_b:
	v_lshl_add_u32 v64, v161, v175, v169
	s_mov_b32 m0, s39
	s_nop 0
	global_load_lds_dwordx4 v64, s[18:19]
	v_lshl_add_u32 v64, v161, v176, v171
	s_add_i32 m0, s39, 0x400
	s_nop 0
	global_load_lds_dwordx4 v64, s[18:19]
	v_lshl_add_u32 v64, v161, v177, v172
	s_add_i32 m0, s39, 0x800
	s_nop 0
	global_load_lds_dwordx4 v64, s[18:19]
	s_mov_b32 m0, s60
	s_nop 0
	global_load_lds_dwordx4 v181, s[18:19]
	s_add_i32 m0, s60, 0x400
	s_nop 0
	global_load_lds_dwordx4 v180, s[18:19]
	s_branch .Lattn_tail_b
